# hyena short-conv phase: the loop-invariant conv weights and biases (48 global loads per iteration) are loaded once before the tile loop and copied from registers
# baseline (speedup 1.0000x reference)
.LBB0_563:
	s_or_b64 exec, exec, s[40:41]
	v_readlane_b32 s2, v255, 18
	v_readlane_b32 s3, v255, 19
	s_xor_b64 s[2:3], s[2:3], -1
	v_writelane_b32 v255, s2, 32
	s_mov_b32 s4, s93
	s_waitcnt lgkmcnt(0)
	v_writelane_b32 v255, s3, 33
	s_mov_b64 s[2:3], s[96:97]
	s_barrier
	s_mov_b32 s5, s94
	v_mov_b32_e32 v0, v192
	s_cmpk_lt_i32 s4, 0x1000
	s_cbranch_scc0 .LBB0_597
	s_load_dwordx2 s[6:7], s[2:3], 0xc8
	s_load_dwordx4 s[8:11], s[2:3], 0x20
	v_readlane_b32 s2, v255, 20
	s_mov_b32 s16, s2
	s_mul_i32 s2, s2, 0x9000
	s_waitcnt lgkmcnt(0)
	s_add_u32 s44, s6, 0xb200000
	s_addc_u32 s45, s7, 0
	s_add_u32 s46, s6, 0x1c200000
	s_addc_u32 s47, s7, 0
	s_add_u32 s48, s6, 0x20200000
	s_addc_u32 s49, s7, 0
	v_readlane_b32 s3, v255, 21
	s_add_u32 s50, s8, s2
	s_mul_i32 s3, s16, 0x3000
	s_addc_u32 s51, s9, 0
	s_add_u32 s54, s10, s3
	v_ashrrev_i32_e32 v81, 3, v0
	s_addc_u32 s55, s11, 0
	v_lshlrev_b32_e32 v0, 3, v0
	v_and_b32_e32 v80, 56, v0
	s_add_u32 s56, s50, 0x3000
	s_movk_i32 s7, 0x41
	s_addc_u32 s57, s51, 0
	v_mad_u64_u32 v[0:1], s[2:3], v81, s7, v[80:81]
	s_add_u32 s58, s50, 0x6000
	v_mad_u32_u24 v1, v80, s7, v81
	s_addc_u32 s59, s51, 0
	s_lshl_b32 s6, s5, 1
	v_or_b32_e32 v82, 0x400, v80
	v_or_b32_e32 v83, 0x800, v80
	v_lshl_add_u32 v84, v1, 2, 0
	v_lshl_add_u32 v85, v0, 2, 0
	s_lshl_b32 s7, s5, 6
	s_lshl_b32 s8, s4, 6
	s_lshl_b32 s9, s5, 7
	s_lshl_b32 s10, s5, 2
	s_lshl_b32 s11, s4, 2
	s_lshl_b32 s16, s5, 3
	v_lshlrev_b32_e32 v194, 1, v80
	s_and_b32 s18, s8, 0x3c0
	v_or_b32_e32 v218, s18, v80
	v_lshlrev_b32_e32 v218, 2, v218
	global_load_dwordx4 v[112:115], v218, s[50:51] offset:16
	global_load_dwordx4 v[116:119], v218, s[50:51]
	global_load_dwordx4 v[120:123], v218, s[56:57] offset:16
	global_load_dwordx4 v[124:127], v218, s[56:57]
	global_load_dwordx4 v[128:131], v218, s[58:59] offset:16
	global_load_dwordx4 v[132:135], v218, s[58:59]
	global_load_dwordx4 v[136:139], v218, s[54:55] offset:16
	global_load_dwordx4 v[140:143], v218, s[54:55]
	v_or_b32_e32 v219, s18, v82
	v_lshlrev_b32_e32 v219, 2, v219
	global_load_dwordx4 v[144:147], v219, s[50:51] offset:16
	global_load_dwordx4 v[148:151], v219, s[50:51]
	global_load_dwordx4 v[152:155], v219, s[56:57] offset:16
	global_load_dwordx4 v[156:159], v219, s[56:57]
	global_load_dwordx4 v[160:163], v219, s[58:59] offset:16
	global_load_dwordx4 v[164:167], v219, s[58:59]
	global_load_dwordx4 v[168:171], v219, s[54:55] offset:16
	global_load_dwordx4 v[172:175], v219, s[54:55]
	v_or_b32_e32 v220, s18, v83
	v_lshlrev_b32_e32 v220, 2, v220
	global_load_dwordx4 v[176:179], v220, s[50:51] offset:16
	global_load_dwordx4 v[180:183], v220, s[50:51]
	global_load_dwordx4 v[184:187], v220, s[56:57] offset:16
	global_load_dwordx4 v[188:191], v220, s[56:57]
	global_load_dwordx4 v[202:205], v220, s[58:59] offset:16
	global_load_dwordx4 v[206:209], v220, s[58:59]
	global_load_dwordx4 v[210:213], v220, s[54:55] offset:16
	global_load_dwordx4 v[214:217], v220, s[54:55]
	s_waitcnt vmcnt(0)
	s_branch .LBB0_566

.LBB0_592:
	v_or_b32_e32 v72, s18, v80
	v_lshlrev_b32_e32 v106, 2, v72
	s_barrier
	s_waitcnt vmcnt(0)
	v_mov_b64_e32 v[72:73], v[112:113]
	v_mov_b64_e32 v[74:75], v[114:115]
	v_mov_b64_e32 v[76:77], v[116:117]
	v_mov_b64_e32 v[78:79], v[118:119]
	v_mov_b64_e32 v[90:91], v[120:121]
	v_mov_b64_e32 v[92:93], v[122:123]
	v_mov_b64_e32 v[86:87], v[124:125]
	v_mov_b64_e32 v[88:89], v[126:127]
	v_mov_b64_e32 v[94:95], v[128:129]
	v_mov_b64_e32 v[96:97], v[130:131]
	v_mov_b64_e32 v[98:99], v[132:133]
	v_mov_b64_e32 v[100:101], v[134:135]
	v_mov_b64_e32 v[102:103], v[136:137]
	v_mov_b64_e32 v[104:105], v[138:139]
	s_nop 0
	v_mov_b64_e32 v[106:107], v[140:141]
	v_mov_b64_e32 v[108:109], v[142:143]
	s_waitcnt vmcnt(10)
	v_lshlrev_b32_e32 v111, 16, v68
	v_and_b32_e32 v68, 0xffff0000, v68
	v_lshlrev_b32_e32 v110, 16, v64
	v_and_b32_e32 v64, 0xffff0000, v64
	s_andn2_b64 vcc, exec, s[60:61]
	s_waitcnt vmcnt(4)
	v_mul_f32_e32 v86, v86, v111
	v_mul_f32_e32 v68, v87, v68
	v_fmac_f32_e32 v86, v76, v110
	v_lshlrev_b32_e32 v76, 16, v60
	v_fmac_f32_e32 v68, v77, v64
	v_and_b32_e32 v60, 0xffff0000, v60
	v_lshlrev_b32_e32 v64, 16, v69
	s_waitcnt vmcnt(2)
	v_fmac_f32_e32 v68, v99, v60
	v_lshlrev_b32_e32 v60, 16, v65
	v_mul_f32_e32 v64, v88, v64
	v_fmac_f32_e32 v64, v78, v60
	v_lshlrev_b32_e32 v60, 16, v61
	v_fmac_f32_e32 v64, v100, v60
	s_waitcnt vmcnt(0)
	v_add_f32_e32 v88, v64, v108
	v_and_b32_e32 v64, 0xffff0000, v69
	v_and_b32_e32 v60, 0xffff0000, v65
	v_mul_f32_e32 v64, v89, v64
	v_fmac_f32_e32 v64, v79, v60
	v_and_b32_e32 v60, 0xffff0000, v61
	v_lshlrev_b32_e32 v61, 16, v70
	v_fmac_f32_e32 v64, v101, v60
	v_lshlrev_b32_e32 v60, 16, v66
	v_mul_f32_e32 v61, v90, v61
	v_fmac_f32_e32 v61, v72, v60
	v_lshlrev_b32_e32 v60, 16, v62
	v_fmac_f32_e32 v61, v94, v60
	v_add_f32_e32 v90, v61, v102
	v_and_b32_e32 v61, 0xffff0000, v70
	v_and_b32_e32 v60, 0xffff0000, v66
	v_mul_f32_e32 v61, v91, v61
	v_fmac_f32_e32 v61, v73, v60
	v_and_b32_e32 v60, 0xffff0000, v62
	v_fmac_f32_e32 v61, v95, v60
	v_add_f32_e32 v91, v61, v103
	v_lshlrev_b32_e32 v61, 16, v71
	v_lshlrev_b32_e32 v60, 16, v67
	v_mul_f32_e32 v61, v92, v61
	v_fmac_f32_e32 v61, v74, v60
	v_lshlrev_b32_e32 v60, 16, v63
	v_fmac_f32_e32 v61, v96, v60
	v_add_f32_e32 v92, v61, v104
	v_and_b32_e32 v61, 0xffff0000, v71
	v_and_b32_e32 v60, 0xffff0000, v67
	v_mul_f32_e32 v61, v93, v61
	v_fmac_f32_e32 v61, v75, v60
	v_and_b32_e32 v60, 0xffff0000, v63
	v_fmac_f32_e32 v61, v97, v60
	v_or_b32_e32 v60, s18, v82
	v_lshlrev_b32_e32 v102, 2, v60
	v_fmac_f32_e32 v86, v98, v76
	v_add_f32_e32 v87, v68, v107
	v_add_f32_e32 v89, v64, v109
	v_add_f32_e32 v93, v61, v105
	v_mov_b64_e32 v[60:61], v[144:145]
	v_mov_b64_e32 v[62:63], v[146:147]
	v_mov_b64_e32 v[64:65], v[148:149]
	v_mov_b64_e32 v[66:67], v[150:151]
	v_mov_b64_e32 v[68:69], v[152:153]
	v_mov_b64_e32 v[70:71], v[154:155]
	v_mov_b64_e32 v[72:73], v[156:157]
	v_mov_b64_e32 v[74:75], v[158:159]
	v_mov_b64_e32 v[76:77], v[160:161]
	v_mov_b64_e32 v[78:79], v[162:163]
	v_mov_b64_e32 v[94:95], v[164:165]
	v_mov_b64_e32 v[96:97], v[166:167]
	v_mov_b64_e32 v[98:99], v[168:169]
	v_mov_b64_e32 v[100:101], v[170:171]
	s_nop 0
	v_mov_b64_e32 v[102:103], v[172:173]
	v_mov_b64_e32 v[104:105], v[174:175]
	v_lshlrev_b32_e32 v107, 16, v56
	v_and_b32_e32 v56, 0xffff0000, v56
	v_add_f32_e32 v86, v86, v106
	v_lshlrev_b32_e32 v106, 16, v48
	v_and_b32_e32 v48, 0xffff0000, v48
	s_waitcnt vmcnt(4)
	v_mul_f32_e32 v72, v72, v107
	v_mul_f32_e32 v56, v73, v56
	v_fmac_f32_e32 v72, v64, v106
	v_lshlrev_b32_e32 v64, 16, v52
	v_fmac_f32_e32 v56, v65, v48
	v_and_b32_e32 v48, 0xffff0000, v52
	v_lshlrev_b32_e32 v52, 16, v57
	s_waitcnt vmcnt(2)
	v_fmac_f32_e32 v56, v95, v48
	v_lshlrev_b32_e32 v48, 16, v49
	v_mul_f32_e32 v52, v74, v52
	v_fmac_f32_e32 v52, v66, v48
	v_lshlrev_b32_e32 v48, 16, v53
	v_fmac_f32_e32 v52, v96, v48
	v_and_b32_e32 v48, 0xffff0000, v49
	v_and_b32_e32 v49, 0xffff0000, v57
	v_mul_f32_e32 v49, v75, v49
	v_fmac_f32_e32 v49, v67, v48
	v_and_b32_e32 v48, 0xffff0000, v53
	v_fmac_f32_e32 v49, v97, v48
	s_waitcnt vmcnt(0)
	v_add_f32_e32 v97, v49, v105
	v_lshlrev_b32_e32 v49, 16, v58
	v_lshlrev_b32_e32 v48, 16, v50
	v_mul_f32_e32 v49, v68, v49
	v_fmac_f32_e32 v49, v60, v48
	v_lshlrev_b32_e32 v48, 16, v54
	v_fmac_f32_e32 v49, v76, v48
	v_add_f32_e32 v98, v49, v98
	v_and_b32_e32 v49, 0xffff0000, v58
	v_and_b32_e32 v48, 0xffff0000, v50
	v_mul_f32_e32 v49, v69, v49
	v_fmac_f32_e32 v49, v61, v48
	v_and_b32_e32 v48, 0xffff0000, v54
	v_fmac_f32_e32 v49, v77, v48
	v_add_f32_e32 v99, v49, v99
	v_lshlrev_b32_e32 v49, 16, v59
	v_lshlrev_b32_e32 v48, 16, v51
	v_mul_f32_e32 v49, v70, v49
	v_fmac_f32_e32 v49, v62, v48
	v_lshlrev_b32_e32 v48, 16, v55
	v_fmac_f32_e32 v49, v78, v48
	v_add_f32_e32 v100, v49, v100
	v_and_b32_e32 v49, 0xffff0000, v59
	v_and_b32_e32 v48, 0xffff0000, v51
	v_mul_f32_e32 v49, v71, v49
	v_fmac_f32_e32 v49, v63, v48
	v_and_b32_e32 v48, 0xffff0000, v55
	v_fmac_f32_e32 v49, v79, v48
	v_or_b32_e32 v48, s18, v83
	v_fmac_f32_e32 v72, v94, v64
	v_lshlrev_b32_e32 v76, 2, v48
	v_add_f32_e32 v94, v72, v102
	v_add_f32_e32 v95, v56, v103
	v_add_f32_e32 v96, v52, v104
	v_add_f32_e32 v101, v49, v101
	v_mov_b64_e32 v[48:49], v[176:177]
	v_mov_b64_e32 v[50:51], v[178:179]
	v_mov_b64_e32 v[64:65], v[180:181]
	v_mov_b64_e32 v[66:67], v[182:183]
	v_mov_b64_e32 v[56:57], v[184:185]
	v_mov_b64_e32 v[58:59], v[186:187]
	v_mov_b64_e32 v[72:73], v[188:189]
	v_mov_b64_e32 v[74:75], v[190:191]
	v_mov_b64_e32 v[52:53], v[202:203]
	v_mov_b64_e32 v[54:55], v[204:205]
	v_mov_b64_e32 v[68:69], v[206:207]
	v_mov_b64_e32 v[70:71], v[208:209]
	v_mov_b64_e32 v[60:61], v[210:211]
	v_mov_b64_e32 v[62:63], v[212:213]
	s_nop 0
	v_mov_b64_e32 v[76:77], v[214:215]
	v_mov_b64_e32 v[78:79], v[216:217]
	v_lshlrev_b32_e32 v103, 16, v44
	v_and_b32_e32 v44, 0xffff0000, v44
	v_lshlrev_b32_e32 v102, 16, v36
	v_and_b32_e32 v36, 0xffff0000, v36
	s_waitcnt vmcnt(4)
	v_mul_f32_e32 v44, v73, v44
	v_fmac_f32_e32 v44, v65, v36
	v_and_b32_e32 v36, 0xffff0000, v40
	s_waitcnt vmcnt(2)
	v_fmac_f32_e32 v44, v69, v36
	v_mul_f32_e32 v72, v72, v103
	s_waitcnt vmcnt(0)
	v_add_f32_e32 v36, v44, v77
	v_lshlrev_b32_e32 v44, 16, v45
	v_fmac_f32_e32 v72, v64, v102
	v_lshlrev_b32_e32 v64, 16, v40
	v_lshlrev_b32_e32 v40, 16, v37
	v_mul_f32_e32 v44, v74, v44
	v_fmac_f32_e32 v44, v66, v40
	v_lshlrev_b32_e32 v40, 16, v41
	v_fmac_f32_e32 v44, v70, v40
	v_add_f32_e32 v40, v44, v78
	v_and_b32_e32 v44, 0xffff0000, v45
	v_and_b32_e32 v37, 0xffff0000, v37
	v_mul_f32_e32 v44, v75, v44
	v_fmac_f32_e32 v44, v67, v37
	v_and_b32_e32 v37, 0xffff0000, v41
	v_fmac_f32_e32 v44, v71, v37
	v_add_f32_e32 v37, v44, v79
	v_lshlrev_b32_e32 v44, 16, v46
	v_lshlrev_b32_e32 v41, 16, v38
	v_mul_f32_e32 v44, v56, v44
	v_fmac_f32_e32 v44, v48, v41
	v_lshlrev_b32_e32 v41, 16, v42
	v_fmac_f32_e32 v44, v52, v41
	v_add_f32_e32 v41, v44, v60
	v_and_b32_e32 v44, 0xffff0000, v46
	v_and_b32_e32 v38, 0xffff0000, v38
	v_mul_f32_e32 v44, v57, v44
	v_fmac_f32_e32 v44, v49, v38
	v_and_b32_e32 v38, 0xffff0000, v42
	v_fmac_f32_e32 v44, v53, v38
	v_add_f32_e32 v38, v44, v61
	v_lshlrev_b32_e32 v44, 16, v47
	v_lshlrev_b32_e32 v42, 16, v39
	v_mul_f32_e32 v44, v58, v44
	v_fmac_f32_e32 v44, v50, v42
	v_lshlrev_b32_e32 v42, 16, v43
	v_fmac_f32_e32 v44, v54, v42
	v_fmac_f32_e32 v72, v68, v64
	v_add_f32_e32 v42, v44, v62
	v_and_b32_e32 v44, 0xffff0000, v47
	v_add_f32_e32 v64, v72, v76
	v_and_b32_e32 v39, 0xffff0000, v39
	v_mul_f32_e32 v44, v59, v44
	v_fmac_f32_e32 v44, v51, v39
	v_and_b32_e32 v39, 0xffff0000, v43
	v_mul_f32_e32 v43, v94, v64
	v_mul_f32_e32 v36, v95, v36
	ds_write2_b32 v84, v43, v36 offset1:65
	v_add_u32_e32 v36, 0x4000, v84
	ds_write2_b32 v36, v86, v87 offset0:64 offset1:129
	v_mul_f32_e32 v36, v96, v40
	v_mul_f32_e32 v37, v97, v37
	ds_write2_b32 v84, v36, v37 offset0:130 offset1:195
	v_add_u32_e32 v36, 0x4200, v84
	v_fmac_f32_e32 v44, v55, v39
	ds_write2_b32 v36, v88, v89 offset0:66 offset1:131
	v_mul_f32_e32 v36, v98, v41
	v_mul_f32_e32 v37, v99, v38
	v_add_u32_e32 v38, 0x400, v84
	v_add_f32_e32 v39, v44, v63
	ds_write2_b32 v38, v36, v37 offset0:4 offset1:69
	v_add_u32_e32 v36, 0x4400, v84
	ds_write2_b32 v36, v90, v91 offset0:68 offset1:133
	v_mul_f32_e32 v36, v100, v42
	v_mul_f32_e32 v37, v101, v39
	ds_write2_b32 v38, v36, v37 offset0:134 offset1:199
	v_add_u32_e32 v36, 0x4600, v84
	ds_write2_b32 v36, v92, v93 offset0:70 offset1:135
	v_cndmask_b32_e64 v36, 0, 1, s[60:61]
	v_cmp_ne_u32_e64 s[40:41], 1, v36
	s_cbranch_vccnz .LBB0_594
	s_add_i32 s2, s7, s8
	s_and_b32 s2, s2, 0x3c0
	v_or_b32_e32 v36, s2, v80
	v_lshlrev_b32_e32 v64, 2, v36
	v_mov_b64_e32 v[36:37], v[112:113]
	v_mov_b64_e32 v[38:39], v[114:115]
	v_mov_b64_e32 v[40:41], v[116:117]
	v_mov_b64_e32 v[42:43], v[118:119]
	v_mov_b64_e32 v[44:45], v[120:121]
	v_mov_b64_e32 v[46:47], v[122:123]
	v_mov_b64_e32 v[48:49], v[124:125]
	v_mov_b64_e32 v[50:51], v[126:127]
	v_mov_b64_e32 v[52:53], v[128:129]
	v_mov_b64_e32 v[54:55], v[130:131]
	v_mov_b64_e32 v[56:57], v[132:133]
	v_mov_b64_e32 v[58:59], v[134:135]
	v_mov_b64_e32 v[60:61], v[136:137]
	v_mov_b64_e32 v[62:63], v[138:139]
	s_nop 0
	v_mov_b64_e32 v[64:65], v[140:141]
	v_mov_b64_e32 v[66:67], v[142:143]
	v_lshlrev_b32_e32 v69, 16, v8
	v_lshlrev_b32_e32 v68, 16, v4
	v_lshlrev_b32_e32 v77, 16, v20
	v_lshlrev_b32_e32 v76, 16, v12
	v_lshlrev_b32_e32 v91, 16, v32
	v_lshlrev_b32_e32 v90, 16, v24
	s_waitcnt vmcnt(4)
	v_mul_f32_e32 v48, v48, v69
	v_fmac_f32_e32 v48, v40, v68
	v_lshlrev_b32_e32 v40, 16, v0
	s_waitcnt vmcnt(2)
	v_fmac_f32_e32 v48, v56, v40
	s_waitcnt vmcnt(0)
	v_add_f32_e32 v68, v48, v64
	v_and_b32_e32 v48, 0xffff0000, v8
	v_and_b32_e32 v40, 0xffff0000, v4
	v_mul_f32_e32 v48, v49, v48
	v_fmac_f32_e32 v48, v41, v40
	v_and_b32_e32 v40, 0xffff0000, v0
	v_lshlrev_b32_e32 v41, 16, v9
	v_fmac_f32_e32 v48, v57, v40
	v_lshlrev_b32_e32 v40, 16, v5
	v_mul_f32_e32 v41, v50, v41
	v_fmac_f32_e32 v41, v42, v40
	v_lshlrev_b32_e32 v40, 16, v1
	v_fmac_f32_e32 v41, v58, v40
	v_add_f32_e32 v70, v41, v66
	v_and_b32_e32 v41, 0xffff0000, v9
	v_and_b32_e32 v40, 0xffff0000, v5
	v_mul_f32_e32 v41, v51, v41
	v_fmac_f32_e32 v41, v43, v40
	v_and_b32_e32 v40, 0xffff0000, v1
	v_fmac_f32_e32 v41, v59, v40
	v_add_f32_e32 v71, v41, v67
	v_lshlrev_b32_e32 v41, 16, v10
	v_lshlrev_b32_e32 v40, 16, v6
	v_mul_f32_e32 v41, v44, v41
	v_fmac_f32_e32 v41, v36, v40
	v_lshlrev_b32_e32 v36, 16, v2
	v_and_b32_e32 v40, 0xffff0000, v10
	v_fmac_f32_e32 v41, v52, v36
	v_and_b32_e32 v36, 0xffff0000, v6
	v_mul_f32_e32 v40, v45, v40
	v_fmac_f32_e32 v40, v37, v36
	v_and_b32_e32 v36, 0xffff0000, v2
	v_lshlrev_b32_e32 v37, 16, v11
	v_fmac_f32_e32 v40, v53, v36
	v_lshlrev_b32_e32 v36, 16, v7
	v_mul_f32_e32 v37, v46, v37
	v_fmac_f32_e32 v37, v38, v36
	v_lshlrev_b32_e32 v36, 16, v3
	v_fmac_f32_e32 v37, v54, v36
	v_add_f32_e32 v74, v37, v62
	v_and_b32_e32 v37, 0xffff0000, v11
	v_and_b32_e32 v36, 0xffff0000, v7
	v_mul_f32_e32 v37, v47, v37
	v_fmac_f32_e32 v37, v39, v36
	v_and_b32_e32 v36, 0xffff0000, v3
	v_fmac_f32_e32 v37, v55, v36
	v_or_b32_e32 v36, s2, v82
	v_lshlrev_b32_e32 v64, 2, v36
	v_add_f32_e32 v69, v48, v65
	v_add_f32_e32 v72, v41, v60
	v_add_f32_e32 v73, v40, v61
	v_add_f32_e32 v75, v37, v63
	v_mov_b64_e32 v[36:37], v[144:145]
	v_mov_b64_e32 v[38:39], v[146:147]
	v_mov_b64_e32 v[40:41], v[148:149]
	v_mov_b64_e32 v[42:43], v[150:151]
	v_mov_b64_e32 v[44:45], v[152:153]
	v_mov_b64_e32 v[46:47], v[154:155]
	v_mov_b64_e32 v[48:49], v[156:157]
	v_mov_b64_e32 v[50:51], v[158:159]
	v_mov_b64_e32 v[52:53], v[160:161]
	v_mov_b64_e32 v[54:55], v[162:163]
	v_mov_b64_e32 v[56:57], v[164:165]
	v_mov_b64_e32 v[58:59], v[166:167]
	v_mov_b64_e32 v[60:61], v[168:169]
	v_mov_b64_e32 v[62:63], v[170:171]
	s_nop 0
	v_mov_b64_e32 v[64:65], v[172:173]
	v_mov_b64_e32 v[66:67], v[174:175]
	s_waitcnt vmcnt(4)
	v_mul_f32_e32 v48, v48, v77
	v_fmac_f32_e32 v48, v40, v76
	v_lshlrev_b32_e32 v40, 16, v16
	s_waitcnt vmcnt(2)
	v_fmac_f32_e32 v48, v56, v40
	s_waitcnt vmcnt(0)
	v_add_f32_e32 v76, v48, v64
	v_and_b32_e32 v48, 0xffff0000, v20
	v_and_b32_e32 v40, 0xffff0000, v12
	v_mul_f32_e32 v48, v49, v48
	v_fmac_f32_e32 v48, v41, v40
	v_and_b32_e32 v40, 0xffff0000, v16
	v_lshlrev_b32_e32 v41, 16, v21
	v_fmac_f32_e32 v48, v57, v40
	v_lshlrev_b32_e32 v40, 16, v13
	v_mul_f32_e32 v41, v50, v41
	v_fmac_f32_e32 v41, v42, v40
	v_lshlrev_b32_e32 v40, 16, v17
	v_fmac_f32_e32 v41, v58, v40
	v_add_f32_e32 v78, v41, v66
	v_and_b32_e32 v41, 0xffff0000, v21
	v_and_b32_e32 v40, 0xffff0000, v13
	v_mul_f32_e32 v41, v51, v41
	v_fmac_f32_e32 v41, v43, v40
	v_and_b32_e32 v40, 0xffff0000, v17
	v_fmac_f32_e32 v41, v59, v40
	v_add_f32_e32 v79, v41, v67
	v_lshlrev_b32_e32 v41, 16, v22
	v_lshlrev_b32_e32 v40, 16, v14
	v_mul_f32_e32 v41, v44, v41
	v_fmac_f32_e32 v41, v36, v40
	v_lshlrev_b32_e32 v36, 16, v18
	v_and_b32_e32 v40, 0xffff0000, v22
	v_fmac_f32_e32 v41, v52, v36
	v_and_b32_e32 v36, 0xffff0000, v14
	v_mul_f32_e32 v40, v45, v40
	v_fmac_f32_e32 v40, v37, v36
	v_and_b32_e32 v36, 0xffff0000, v18
	v_lshlrev_b32_e32 v37, 16, v23
	v_fmac_f32_e32 v40, v53, v36
	v_lshlrev_b32_e32 v36, 16, v15
	v_mul_f32_e32 v37, v46, v37
	v_fmac_f32_e32 v37, v38, v36
	v_lshlrev_b32_e32 v36, 16, v19
	v_fmac_f32_e32 v37, v54, v36
	v_add_f32_e32 v88, v37, v62
	v_and_b32_e32 v37, 0xffff0000, v23
	v_and_b32_e32 v36, 0xffff0000, v15
	v_mul_f32_e32 v37, v47, v37
	v_fmac_f32_e32 v37, v39, v36
	v_and_b32_e32 v36, 0xffff0000, v19
	v_fmac_f32_e32 v37, v55, v36
	v_or_b32_e32 v36, s2, v83
	v_lshlrev_b32_e32 v64, 2, v36
	v_add_f32_e32 v77, v48, v65
	v_add_f32_e32 v86, v41, v60
	v_add_f32_e32 v87, v40, v61
	v_add_f32_e32 v89, v37, v63
	v_mov_b64_e32 v[36:37], v[176:177]
	v_mov_b64_e32 v[38:39], v[178:179]
	v_mov_b64_e32 v[52:53], v[180:181]
	v_mov_b64_e32 v[54:55], v[182:183]
	v_mov_b64_e32 v[44:45], v[184:185]
	v_mov_b64_e32 v[46:47], v[186:187]
	v_mov_b64_e32 v[60:61], v[188:189]
	v_mov_b64_e32 v[62:63], v[190:191]
	v_mov_b64_e32 v[40:41], v[202:203]
	v_mov_b64_e32 v[42:43], v[204:205]
	v_mov_b64_e32 v[56:57], v[206:207]
	v_mov_b64_e32 v[58:59], v[208:209]
	v_mov_b64_e32 v[48:49], v[210:211]
	v_mov_b64_e32 v[50:51], v[212:213]
	s_nop 0
	v_mov_b64_e32 v[64:65], v[214:215]
	v_mov_b64_e32 v[66:67], v[216:217]
	s_waitcnt vmcnt(4)
	v_mul_f32_e32 v60, v60, v91
	v_fmac_f32_e32 v60, v52, v90
	v_lshlrev_b32_e32 v52, 16, v28
	s_waitcnt vmcnt(2)
	v_fmac_f32_e32 v60, v56, v52
	s_waitcnt vmcnt(0)
	v_add_f32_e32 v52, v60, v64
	v_and_b32_e32 v60, 0xffff0000, v32
	v_and_b32_e32 v56, 0xffff0000, v24
	v_mul_f32_e32 v60, v61, v60
	v_fmac_f32_e32 v60, v53, v56
	v_and_b32_e32 v53, 0xffff0000, v28
	v_fmac_f32_e32 v60, v57, v53
	v_lshlrev_b32_e32 v57, 16, v33
	v_lshlrev_b32_e32 v56, 16, v25
	v_mul_f32_e32 v57, v62, v57
	v_fmac_f32_e32 v57, v54, v56
	v_lshlrev_b32_e32 v54, 16, v29
	v_fmac_f32_e32 v57, v58, v54
	v_add_f32_e32 v54, v57, v66
	v_and_b32_e32 v57, 0xffff0000, v33
	v_and_b32_e32 v56, 0xffff0000, v25
	v_mul_f32_e32 v57, v63, v57
	v_fmac_f32_e32 v57, v55, v56
	v_and_b32_e32 v55, 0xffff0000, v29
	v_fmac_f32_e32 v57, v59, v55
	v_add_f32_e32 v55, v57, v67
	v_lshlrev_b32_e32 v57, 16, v34
	v_lshlrev_b32_e32 v56, 16, v26
	v_mul_f32_e32 v44, v44, v57
	v_fmac_f32_e32 v44, v36, v56
	v_lshlrev_b32_e32 v36, 16, v30
	v_fmac_f32_e32 v44, v40, v36
	v_add_f32_e32 v36, v44, v48
	v_and_b32_e32 v44, 0xffff0000, v34
	v_and_b32_e32 v40, 0xffff0000, v26
	v_mul_f32_e32 v44, v45, v44
	v_fmac_f32_e32 v44, v37, v40
	v_and_b32_e32 v37, 0xffff0000, v30
	v_fmac_f32_e32 v44, v41, v37
	v_lshlrev_b32_e32 v41, 16, v35
	v_lshlrev_b32_e32 v40, 16, v27
	v_mul_f32_e32 v41, v46, v41
	v_fmac_f32_e32 v41, v38, v40
	v_lshlrev_b32_e32 v38, 16, v31
	v_fmac_f32_e32 v41, v42, v38
	v_add_f32_e32 v38, v41, v50
	v_and_b32_e32 v41, 0xffff0000, v35
	v_and_b32_e32 v40, 0xffff0000, v27
	v_mul_f32_e32 v41, v47, v41
	v_fmac_f32_e32 v41, v39, v40
	v_and_b32_e32 v39, 0xffff0000, v31
	v_add_f32_e32 v53, v60, v65
	v_fmac_f32_e32 v41, v43, v39
	v_add_f32_e32 v37, v44, v49
	v_add_f32_e32 v39, v41, v51
	v_mul_f32_e32 v40, v76, v52
	v_mul_f32_e32 v41, v77, v53
	v_add_u32_e32 v42, 0x8000, v84
	ds_write2_b32 v42, v40, v41 offset0:128 offset1:193
	v_add_u32_e32 v42, 0x8400, v84
	v_mul_f32_e32 v36, v86, v36
	v_mul_f32_e32 v37, v87, v37
	v_add_u32_e32 v40, 0xc200, v84
	ds_write2_b32 v42, v36, v37 offset0:132 offset1:197
	v_add_u32_e32 v36, 0xc600, v84
	ds_write2_b32 v40, v68, v69 offset0:64 offset1:129
	v_mul_f32_e32 v40, v78, v54
	v_mul_f32_e32 v41, v79, v55
	ds_write2_b32 v36, v72, v73 offset0:68 offset1:133
	v_mul_f32_e32 v36, v88, v38
	v_mul_f32_e32 v37, v89, v39
	v_add_u32_e32 v38, 0x8800, v84
	ds_write2_b32 v42, v40, v41 offset0:2 offset1:67
	v_add_u32_e32 v40, 0xc400, v84
	ds_write2_b32 v38, v36, v37 offset0:6 offset1:71
	v_add_u32_e32 v36, 0xc800, v84
	ds_write2_b32 v40, v70, v71 offset0:66 offset1:131
	ds_write2_b32 v36, v74, v75 offset0:70 offset1:135
